# t24 + softmax exponent FMAs packed pairwise (v_pk_fma_f32, in place) in the two unmasked attention step variants
# speedup vs baseline: 1.0058x; 1.0015x over previous
; #define LAS __attribute__((address_space(3)))
; #define MFMA32(a, b, c) __builtin_amdgcn_mfma_f32_32x32x16_bf16((a), (b), (c), 0, 0, 0)
; #define WG_BAR() do { asm volatile("s_waitcnt lgkmcnt(0)" ::: "memory"); __builtin_amdgcn_s_barrier(); asm volatile("" ::: "memory"); } while (0)
; template <class ScoreFn>
; __device__ __forceinline__ void attn_step(AttnState& st, const bf16x8 (&qf)[4], LAS unsigned char* kb, LAS unsigned char* vb, int lane, const ScoreFn& sf) {
;     ...
;     LAS unsigned char* kp = kb + r * KVP; const int kx = (h ^ (r & 7)) << 4;
; #pragma unroll
;     for (int ds = 0; ds < 4; ++ds) {
;         const bf16x8 k0 = *(const LAS bf16x8*)(kp + (kx ^ (ds << 5))), k1 = *(const LAS bf16x8*)(kp + 32 * KVP + (kx ^ (ds << 5)));
;         s0 = MFMA32(k0, qf[ds], s0); s1 = MFMA32(k1, qf[ds], s1);
;     }
;     float mt = NEG_BIG;
;     __builtin_amdgcn_sched_barrier(0);
; #pragma unroll
;     for (int i = 0; i < 16; ++i) { s0[i] = sf(s0[i], (i & 3) + 8 * (i >> 2), h, r); mt = fmaxf(mt, s0[i]); if ((i & 7) == 7) __builtin_amdgcn_sched_barrier(0); }
; #pragma unroll
;     for (int i = 0; i < 16; ++i) { s1[i] = sf(s1[i], 32 + (i & 3) + 8 * (i >> 2), h, r); mt = fmaxf(mt, s1[i]); if ((i & 7) == 7) __builtin_amdgcn_sched_barrier(0); }
;     mt = fmaxf(mt, __shfl_xor(mt, 32));
; template <bool ISB>
; __device__ __forceinline__ void attn_wg_item(Frame& F, int l, int idx) {
;     ...
;     AttnState st;
; #pragma unroll
;     for (int i = 0; i < 16; ++i) { st.o0[i] = 0.f; st.o1[i] = 0.f; }
;     st.m = NEG_BIG; st.l = 0.f;
; #pragma unroll
;     for (int t = 0; t < ATT_D; ++t) ATT_DMA(t);
;     if (ISB && lat) {
;         const float* bsrc = KIN(I_NBBIAS) + (size_t)(l * 8 + (ix & 7)) * 465;
;         if (tid < 465) tab[64 + tid] = bsrc[tid] * LOG2E; }
;     for (int s = 0; s < NS; ++s) {
;         ATT_DMA(s + ATT_D);
;         asm volatile("s_waitcnt vmcnt(8)" ::: "memory");
;         WG_BAR();
;         LAS unsigned char* cur = ring + (s % ATT_NB) * KV_BUF;
;         if (s >= nloc) { ScorePlain sf; attn_step(st, qf, cur, cur + KV_TILE, lane, sf); }
.LBB0_581:
	s_mul_hi_u32 s1, s16, 0xaaaaaaab
	s_mul_hi_u32 s2, s13, 0xaaaaaaab
	s_lshr_b32 s1, s1, 2
	s_lshr_b32 s2, s2, 2
	s_mul_i32 s1, s1, 0x18000
	s_mul_i32 s2, s2, 0x18000
	v_readlane_b32 s3, v253, 15
	s_sub_i32 s1, s15, s1
	v_add3_u32 v126, s1, v104, v89
	v_add3_u32 v125, s1, v96, v89
	v_add3_u32 v127, s1, v103, v89
	v_add3_u32 v124, s1, v95, v89
	v_add3_u32 v122, s1, v102, v89
	v_add3_u32 v123, s1, v101, v89
	v_add3_u32 v119, s1, v94, v89
	v_add3_u32 v120, s1, v93, v89
	v_add3_u32 v117, s1, v100, v89
	v_add3_u32 v118, s1, v99, v89
	v_add3_u32 v115, s1, v92, v89
	v_add3_u32 v116, s1, v91, v89
	v_add3_u32 v113, s1, v98, v89
	v_add3_u32 v114, s1, v97, v89
	v_add3_u32 v111, s1, v90, v89
	v_add3_u32 v112, s1, v88, v89
	v_add_u32_e32 v128, s1, v105
	s_sub_i32 s8, s3, s2
	v_add_u32_e32 v130, s1, v106
	v_add_u32_e32 v131, s1, v107
	v_add_u32_e32 v132, s1, v108
	s_add_i32 s1, s16, 4
	s_cmp_lt_i32 s16, s11
	s_cselect_b64 s[2:3], -1, 0
	s_and_b64 vcc, s[2:3], exec
	s_cselect_b32 s1, s1, s12
	s_cmp_lt_i32 s1, s11
	s_cselect_b32 s2, 0, s11
	s_cselect_b32 s3, s10, 0x2000
	s_sub_i32 s1, s1, s2
	s_lshl_b32 s1, s1, 6
	s_add_i32 s1, s1, s3
	s_add_i32 s2, s15, s8
	v_mov_b32_e32 v84, v2
	v_mov_b32_e32 v85, v3
	s_add_i32 s8, s2, 0
	v_mad_i64_i32 v[2:3], s[2:3], s1, v249, v[50:51]
	s_add_i32 m0, s8, 0x10000
	v_lshl_add_u64 v[4:5], v[2:3], 0, s[18:19]
	global_load_lds_dwordx4 v[4:5], off
	v_lshl_add_u64 v[2:3], v[2:3], 0, s[20:21]
	s_add_i32 m0, s8, 0x12000
	v_mov_b32_e32 v82, v18
	global_load_lds_dwordx4 v[2:3], off
	s_waitcnt vmcnt(8)
	s_waitcnt lgkmcnt(0)
	s_barrier
	v_mov_b32_e32 v83, v19
	s_mov_b64 s[8:9], -1
	s_cbranch_vccnz .LBB0_583
	s_mov_b32 s1, 0
	v_add_u32_e32 v6, s1, v132
	ds_read_b128 v[2:5], v6
	ds_read_b128 v[18:21], v6 offset:4096
	v_add_u32_e32 v26, s1, v131
	ds_read_b128 v[22:25], v26
	ds_read_b128 v[134:137], v26 offset:4096
	v_add_u32_e32 v27, s1, v130
	v_add_u32_e32 v26, s1, v128
	s_waitcnt lgkmcnt(0)
	v_mfma_f32_32x32x16_bf16 v[2:17], v[2:5], v[34:37], 0
	ds_read_b128 v[138:141], v27 offset:4096
	v_mfma_f32_32x32x16_bf16 v[2:17], v[22:25], v[38:41], v[2:17]
	ds_read_b128 v[22:25], v27
	s_waitcnt lgkmcnt(0)
	v_mfma_f32_32x32x16_bf16 v[2:17], v[22:25], v[42:45], v[2:17]
	ds_read_b128 v[22:25], v26
	ds_read_b128 v[142:145], v26 offset:4096
	s_waitcnt lgkmcnt(0)
	v_mfma_f32_32x32x16_bf16 v[2:17], v[22:25], v[46:49], v[2:17]
	v_mfma_f32_32x32x16_bf16 v[18:33], v[18:21], v[34:37], 0
	v_mfma_f32_32x32x16_bf16 v[18:33], v[134:137], v[38:41], v[18:33]
	v_mfma_f32_32x32x16_bf16 v[18:33], v[138:141], v[42:45], v[18:33]
	v_mfma_f32_32x32x16_bf16 v[18:33], v[142:145], v[46:49], v[18:33]
	s_nop 7
	s_mov_b32 s1, 0xf149f2ca
	v_max3_f32 v66, v2, v3, v4
	v_max3_f32 v66, v66, v5, v6
	v_max3_f32 v66, v66, v7, v8
	v_max3_f32 v66, v66, v9, v10
	v_max3_f32 v66, v66, v11, v12
	v_max3_f32 v66, v66, v13, v14
	v_max3_f32 v66, v66, v15, v16
	v_max3_f32 v66, v66, v17, v18
	v_max3_f32 v66, v66, v19, v20
	v_max3_f32 v66, v66, v21, v22
	v_max3_f32 v66, v66, v23, v24
	v_max3_f32 v66, v66, v25, v26
	v_max3_f32 v66, v66, v27, v28
	v_max3_f32 v66, v66, v29, v30
	v_max3_f32 v66, v66, v31, v32
	v_max_f32_e32 v66, v66, v33
	v_cmp_lt_i32_e32 vcc, v242, v241
	v_mul_f32_e32 v66, 0x3e38aa3b, v66
	v_max_f32_e32 v66, s1, v66
	v_cndmask_b32_e32 v121, v240, v242, vcc
	v_lshlrev_b32_e32 v121, 2, v121
	ds_bpermute_b32 v121, v121, v66
	s_waitcnt lgkmcnt(0)
; #define LAS __attribute__((address_space(3)))
; #define MFMA32(a, b, c) __builtin_amdgcn_mfma_f32_32x32x16_bf16((a), (b), (c), 0, 0, 0)
; __device__ __forceinline__ unsigned cvtpk(float lo, float hi) { return pg8::cvt_pk_bf16(lo, hi); }
; template <class ScoreFn>
; __device__ __forceinline__ void attn_step(AttnState& st, const bf16x8 (&qf)[4], LAS unsigned char* kb, LAS unsigned char* vb, int lane, const ScoreFn& sf) {
;     ...
;     mt = fmaxf(mt, __shfl_xor(mt, 32));
;     const float mn = fmaxf(st.m, mt), alpha = __builtin_amdgcn_exp2f(st.m - mn);
;     float ps = 0.f;
; #pragma unroll
;     for (int i = 0; i < 16; ++i) { s0[i] = __builtin_amdgcn_exp2f(s0[i] - mn); s1[i] = __builtin_amdgcn_exp2f(s1[i] - mn); ps += s0[i] + s1[i]; }
;     st.l = st.l * alpha + ps; st.m = mn;
; #pragma unroll
;     for (int i = 0; i < 16; ++i) { st.o0[i] *= alpha; st.o1[i] *= alpha; }
;     __builtin_amdgcn_sched_barrier(0);
;     v4u pw[4];
;     pw[0].x = cvtpk(s0[0], s0[1]); pw[0].y = cvtpk(s0[2], s0[3]); pw[0].z = cvtpk(s0[4], s0[5]); pw[0].w = cvtpk(s0[6], s0[7]);
;     pw[1].x = cvtpk(s0[8], s0[9]); pw[1].y = cvtpk(s0[10], s0[11]); pw[1].z = cvtpk(s0[12], s0[13]); pw[1].w = cvtpk(s0[14], s0[15]);
;     pw[2].x = cvtpk(s1[0], s1[1]); pw[2].y = cvtpk(s1[2], s1[3]); pw[2].z = cvtpk(s1[4], s1[5]); pw[2].w = cvtpk(s1[6], s1[7]);
;     pw[3].x = cvtpk(s1[8], s1[9]); pw[3].y = cvtpk(s1[10], s1[11]); pw[3].z = cvtpk(s1[12], s1[13]); pw[3].w = cvtpk(s1[14], s1[15]);
;     const int i16 = lane & 15, q = i16 >> 2, p = i16 & 3, dhalf = (lane >> 4) & 1;
;     LAS unsigned char* vrow = vb + (4 * h + q) * KVP + (p & 1) * 8;
;     LAS unsigned char* vp0 = vrow + (((2 * dhalf + (p >> 1)) ^ (4 * h + q)) << 4); LAS unsigned char* vp1 = vrow + (((4 + 2 * dhalf + (p >> 1)) ^ (4 * h + q)) << 4);
; #pragma unroll
;     for (int ks = 0; ks < 4; ++ks) {
;         const s16x4 l0 = tr_read(vp0 + (16 * ks) * KVP), h0 = tr_read(vp0 + (16 * ks + 8) * KVP);
;         const s16x4 l1 = tr_read(vp1 + (16 * ks) * KVP), h1 = tr_read(vp1 + (16 * ks + 8) * KVP);
;         const bf16x8 v0 = (bf16x8){l0[0], l0[1], l0[2], l0[3], h0[0], h0[1], h0[2], h0[3]};
;         const bf16x8 v1 = (bf16x8){l1[0], l1[1], l1[2], l1[3], h1[0], h1[1], h1[2], h1[3]};
;         const bf16x8 pf = __builtin_bit_cast(bf16x8, pw[ks]);
;         st.o0 = MFMA32(v0, pf, st.o0); st.o1 = MFMA32(v1, pf, st.o1);
;     }
	v_max3_f32 v121, v110, v66, v121
	v_pk_fma_f32 v[2:3], v[2:3], s[0:1], v[120:121] op_sel:[0,0,1] op_sel_hi:[1,0,1] neg_lo:[0,0,1] neg_hi:[0,0,1]
	v_pk_fma_f32 v[18:19], v[18:19], s[0:1], v[120:121] op_sel:[0,0,1] op_sel_hi:[1,0,1] neg_lo:[0,0,1] neg_hi:[0,0,1]
	v_exp_f32_e32 v133, v2
	v_exp_f32_e32 v165, v18
	v_exp_f32_e32 v66, v3
	v_exp_f32_e32 v142, v19
	v_add_f32_e32 v143, v165, v133
	v_pk_add_f32 v[2:3], v[142:143], v[66:67]
	s_nop 0
	v_pk_add_f32 v[136:137], v[2:3], v[2:3] op_sel_hi:[0,1]
	v_pk_fma_f32 v[4:5], v[4:5], s[0:1], v[120:121] op_sel:[0,0,1] op_sel_hi:[1,0,1] neg_lo:[0,0,1] neg_hi:[0,0,1]
	v_pk_fma_f32 v[20:21], v[20:21], s[0:1], v[120:121] op_sel:[0,0,1] op_sel_hi:[1,0,1] neg_lo:[0,0,1] neg_hi:[0,0,1]
	v_exp_f32_e32 v135, v4
	v_exp_f32_e32 v143, v20
	v_exp_f32_e32 v136, v5
	v_exp_f32_e32 v144, v21
	v_add_f32_e32 v145, v143, v135
	v_pk_add_f32 v[2:3], v[144:145], v[136:137]
	s_nop 0
	v_pk_add_f32 v[138:139], v[2:3], v[2:3] op_sel_hi:[0,1]
	v_pk_fma_f32 v[6:7], v[6:7], s[0:1], v[120:121] op_sel:[0,0,1] op_sel_hi:[1,0,1] neg_lo:[0,0,1] neg_hi:[0,0,1]
	v_pk_fma_f32 v[22:23], v[22:23], s[0:1], v[120:121] op_sel:[0,0,1] op_sel_hi:[1,0,1] neg_lo:[0,0,1] neg_hi:[0,0,1]
	v_exp_f32_e32 v137, v6
	v_exp_f32_e32 v145, v22
	v_exp_f32_e32 v138, v7
	v_exp_f32_e32 v146, v23
	v_add_f32_e32 v147, v145, v137
	v_pk_add_f32 v[2:3], v[146:147], v[138:139]
	s_nop 0
	v_pk_add_f32 v[140:141], v[2:3], v[2:3] op_sel_hi:[0,1]
	v_pk_fma_f32 v[8:9], v[8:9], s[0:1], v[120:121] op_sel:[0,0,1] op_sel_hi:[1,0,1] neg_lo:[0,0,1] neg_hi:[0,0,1]
	v_pk_fma_f32 v[24:25], v[24:25], s[0:1], v[120:121] op_sel:[0,0,1] op_sel_hi:[1,0,1] neg_lo:[0,0,1] neg_hi:[0,0,1]
	v_exp_f32_e32 v139, v8
	v_exp_f32_e32 v147, v24
	v_exp_f32_e32 v140, v9
	v_exp_f32_e32 v148, v25
	v_add_f32_e32 v149, v147, v139
	v_pk_add_f32 v[2:3], v[148:149], v[140:141]
	s_nop 0
	v_pk_add_f32 v[150:151], v[2:3], v[2:3] op_sel_hi:[0,1]
	v_pk_fma_f32 v[10:11], v[10:11], s[0:1], v[120:121] op_sel:[0,0,1] op_sel_hi:[1,0,1] neg_lo:[0,0,1] neg_hi:[0,0,1]
	v_pk_fma_f32 v[26:27], v[26:27], s[0:1], v[120:121] op_sel:[0,0,1] op_sel_hi:[1,0,1] neg_lo:[0,0,1] neg_hi:[0,0,1]
	v_exp_f32_e32 v141, v10
	v_exp_f32_e32 v149, v26
	v_exp_f32_e32 v150, v11
	v_exp_f32_e32 v152, v27
	v_add_f32_e32 v153, v149, v141
	v_pk_add_f32 v[2:3], v[152:153], v[150:151]
	s_nop 0
	v_pk_add_f32 v[154:155], v[2:3], v[2:3] op_sel_hi:[0,1]
	v_pk_fma_f32 v[12:13], v[12:13], s[0:1], v[120:121] op_sel:[0,0,1] op_sel_hi:[1,0,1] neg_lo:[0,0,1] neg_hi:[0,0,1]
	v_pk_fma_f32 v[28:29], v[28:29], s[0:1], v[120:121] op_sel:[0,0,1] op_sel_hi:[1,0,1] neg_lo:[0,0,1] neg_hi:[0,0,1]
	v_exp_f32_e32 v151, v12
	v_exp_f32_e32 v153, v28
	v_exp_f32_e32 v154, v13
	v_exp_f32_e32 v156, v29
	v_add_f32_e32 v157, v153, v151
	v_pk_add_f32 v[2:3], v[156:157], v[154:155]
	s_nop 0
	v_pk_add_f32 v[158:159], v[2:3], v[2:3] op_sel_hi:[0,1]
	v_pk_fma_f32 v[14:15], v[14:15], s[0:1], v[120:121] op_sel:[0,0,1] op_sel_hi:[1,0,1] neg_lo:[0,0,1] neg_hi:[0,0,1]
	v_pk_fma_f32 v[30:31], v[30:31], s[0:1], v[120:121] op_sel:[0,0,1] op_sel_hi:[1,0,1] neg_lo:[0,0,1] neg_hi:[0,0,1]
	v_exp_f32_e32 v155, v14
	v_exp_f32_e32 v157, v30
	v_exp_f32_e32 v158, v15
	v_exp_f32_e32 v160, v31
	v_add_f32_e32 v161, v157, v155
	v_pk_add_f32 v[2:3], v[160:161], v[158:159]
	s_nop 0
	v_pk_add_f32 v[162:163], v[2:3], v[2:3] op_sel_hi:[0,1]
	v_pk_fma_f32 v[16:17], v[16:17], s[0:1], v[120:121] op_sel:[0,0,1] op_sel_hi:[1,0,1] neg_lo:[0,0,1] neg_hi:[0,0,1]
	v_pk_fma_f32 v[32:33], v[32:33], s[0:1], v[120:121] op_sel:[0,0,1] op_sel_hi:[1,0,1] neg_lo:[0,0,1] neg_hi:[0,0,1]
	v_exp_f32_e32 v159, v16
	v_exp_f32_e32 v161, v32
	v_exp_f32_e32 v162, v17
	v_exp_f32_e32 v166, v33
	v_sub_f32_e32 v2, v110, v121
	v_exp_f32_e32 v18, v2
	v_add_f32_e32 v167, v161, v159
	v_pk_add_f32 v[2:3], v[166:167], v[162:163]
	v_pk_mul_f32 v[16:17], v[80:81], v[18:19] op_sel_hi:[1,0]
	v_add_f32_e32 v129, v2, v3
	v_fmac_f32_e32 v129, v109, v18
	v_pk_mul_f32 v[14:15], v[76:77], v[18:19] op_sel_hi:[1,0]
	v_pk_mul_f32 v[12:13], v[72:73], v[18:19] op_sel_hi:[1,0]
	v_pk_mul_f32 v[10:11], v[68:69], v[18:19] op_sel_hi:[1,0]
	v_pk_mul_f32 v[8:9], v[62:63], v[18:19] op_sel_hi:[1,0]
	v_pk_mul_f32 v[6:7], v[58:59], v[18:19] op_sel_hi:[1,0]
	v_pk_mul_f32 v[4:5], v[54:55], v[18:19] op_sel_hi:[1,0]
	v_pk_mul_f32 v[2:3], v[84:85], v[18:19] op_sel_hi:[1,0]
	v_pk_mul_f32 v[32:33], v[78:79], v[18:19] op_sel_hi:[1,0]
	v_pk_mul_f32 v[30:31], v[74:75], v[18:19] op_sel_hi:[1,0]
	v_pk_mul_f32 v[28:29], v[70:71], v[18:19] op_sel_hi:[1,0]
	v_pk_mul_f32 v[26:27], v[64:65], v[18:19] op_sel_hi:[1,0]
	v_pk_mul_f32 v[24:25], v[60:61], v[18:19] op_sel_hi:[1,0]
	v_pk_mul_f32 v[22:23], v[56:57], v[18:19] op_sel_hi:[1,0]
	v_pk_mul_f32 v[20:21], v[52:53], v[18:19] op_sel_hi:[1,0]
	v_pk_mul_f32 v[18:19], v[82:83], v[18:19] op_sel_hi:[1,0]
	v_cvt_pk_bf16_f32 v135, v135, v136
	v_cvt_pk_bf16_f32 v136, v137, v138
	v_cvt_pk_bf16_f32 v137, v139, v140
	v_cvt_pk_bf16_f32 v138, v141, v150
	v_cvt_pk_bf16_f32 v139, v151, v154
	v_cvt_pk_bf16_f32 v140, v155, v158
	v_cvt_pk_bf16_f32 v143, v143, v144
	v_cvt_pk_bf16_f32 v144, v145, v146
	v_cvt_pk_bf16_f32 v145, v147, v148
	v_cvt_pk_bf16_f32 v146, v149, v152
	v_cvt_pk_bf16_f32 v147, v153, v156
	v_cvt_pk_bf16_f32 v148, v157, v160
	ds_read_b64_tr_b16 v[150:151], v126
	ds_read_b64_tr_b16 v[152:153], v127
	ds_read_b64_tr_b16 v[154:155], v125
	ds_read_b64_tr_b16 v[156:157], v124
	v_cvt_pk_bf16_f32 v134, v133, v66
	v_cvt_pk_bf16_f32 v141, v159, v162
	v_cvt_pk_bf16_f32 v142, v165, v142
	s_waitcnt lgkmcnt(2)
	v_mfma_f32_32x32x16_bf16 v[2:17], v[150:153], v[134:137], v[2:17]
	v_cvt_pk_bf16_f32 v149, v161, v166
	s_mov_b64 s[8:9], 0
	s_waitcnt lgkmcnt(0)
	v_mfma_f32_32x32x16_bf16 v[18:33], v[154:157], v[134:137], v[18:33]
	ds_read_b64_tr_b16 v[134:135], v122
	ds_read_b64_tr_b16 v[136:137], v123
	ds_read_b64_tr_b16 v[150:151], v119
	ds_read_b64_tr_b16 v[152:153], v120
	s_waitcnt lgkmcnt(2)
	v_mfma_f32_32x32x16_bf16 v[2:17], v[134:137], v[138:141], v[2:17]
	s_waitcnt lgkmcnt(0)
	v_mfma_f32_32x32x16_bf16 v[18:33], v[150:153], v[138:141], v[18:33]
	ds_read_b64_tr_b16 v[134:135], v117
	ds_read_b64_tr_b16 v[136:137], v118
	ds_read_b64_tr_b16 v[138:139], v115
	ds_read_b64_tr_b16 v[140:141], v116
	s_waitcnt lgkmcnt(2)
	v_mfma_f32_32x32x16_bf16 v[2:17], v[134:137], v[142:145], v[2:17]
	s_waitcnt lgkmcnt(0)
	v_mfma_f32_32x32x16_bf16 v[18:33], v[138:141], v[142:145], v[18:33]
	ds_read_b64_tr_b16 v[134:135], v113
	ds_read_b64_tr_b16 v[136:137], v114
	ds_read_b64_tr_b16 v[138:139], v111
	ds_read_b64_tr_b16 v[140:141], v112
	s_waitcnt lgkmcnt(2)
	v_mfma_f32_32x32x16_bf16 v[2:17], v[134:137], v[146:149], v[2:17]
	s_waitcnt lgkmcnt(0)
	v_mfma_f32_32x32x16_bf16 v[18:33], v[138:141], v[146:149], v[18:33]

; #define LAS __attribute__((address_space(3)))
; #define MFMA32(a, b, c) __builtin_amdgcn_mfma_f32_32x32x16_bf16((a), (b), (c), 0, 0, 0)
; #define WG_BAR() do { asm volatile("s_waitcnt lgkmcnt(0)" ::: "memory"); __builtin_amdgcn_s_barrier(); asm volatile("" ::: "memory"); } while (0)
; #define ATT_DMA(t) do { const int t_ = (t) < NS ? (t) : NS - 1; const size_t ro_ = (size_t)TILE_ROW(t_) * ZC; LAS unsigned char* d_ = dk0 + ((t) % ATT_NB) * KV_BUF; \
;         __builtin_amdgcn_global_load_lds((const unsigned*)(gk + ro_), (LAS unsigned*)d_, 16, 0, 0); __builtin_amdgcn_global_load_lds((const unsigned*)(gv + ro_), (LAS unsigned*)(d_ + KV_TILE), 16, 0, 0); } while (0)
; template <class ScoreFn>
; __device__ __forceinline__ void attn_step(AttnState& st, const bf16x8 (&qf)[4], LAS unsigned char* kb, LAS unsigned char* vb, int lane, const ScoreFn& sf) {
;     ...
;     LAS unsigned char* kp = kb + r * KVP; const int kx = (h ^ (r & 7)) << 4;
; #pragma unroll
;     for (int ds = 0; ds < 4; ++ds) {
;         const bf16x8 k0 = *(const LAS bf16x8*)(kp + (kx ^ (ds << 5))), k1 = *(const LAS bf16x8*)(kp + 32 * KVP + (kx ^ (ds << 5)));
;         s0 = MFMA32(k0, qf[ds], s0); s1 = MFMA32(k1, qf[ds], s1);
;     }
;     float mt = NEG_BIG;
;     __builtin_amdgcn_sched_barrier(0);
; #pragma unroll
;     for (int i = 0; i < 16; ++i) { s0[i] = sf(s0[i], (i & 3) + 8 * (i >> 2), h, r); mt = fmaxf(mt, s0[i]); if ((i & 7) == 7) __builtin_amdgcn_sched_barrier(0); }
; #pragma unroll
;     for (int i = 0; i < 16; ++i) { s1[i] = sf(s1[i], 32 + (i & 3) + 8 * (i >> 2), h, r); mt = fmaxf(mt, s1[i]); if ((i & 7) == 7) __builtin_amdgcn_sched_barrier(0); }
;     mt = fmaxf(mt, __shfl_xor(mt, 32));
; template <bool ISB>
; __device__ __forceinline__ void attn_wg_item(Frame& F, int l, int idx) {
;     ...
;     AttnState st;
; #pragma unroll
;     for (int i = 0; i < 16; ++i) { st.o0[i] = 0.f; st.o1[i] = 0.f; }
;     st.m = NEG_BIG; st.l = 0.f;
; #pragma unroll
;     for (int t = 0; t < ATT_D; ++t) ATT_DMA(t);
;     if (ISB && lat) {
;         const float* bsrc = KIN(I_NBBIAS) + (size_t)(l * 8 + (ix & 7)) * 465;
;         if (tid < 465) tab[64 + tid] = bsrc[tid] * LOG2E; }
;     for (int s = 0; s < NS; ++s) {
;         ATT_DMA(s + ATT_D);
;         asm volatile("s_waitcnt vmcnt(8)" ::: "memory");
;         WG_BAR();
;         LAS unsigned char* cur = ring + (s % ATT_NB) * KV_BUF;
.LBB0_618:
	s_mul_hi_u32 s1, s80, 0xaaaaaaab
	s_lshr_b32 s1, s1, 2
	s_mul_i32 s1, s1, 0x18000
	v_readlane_b32 s2, v253, 14
	s_sub_i32 s74, s2, s1
	v_readlane_b32 s2, v253, 16
	s_sub_i32 s1, s2, s1
	s_mul_hi_u32 s2, s82, 0xaaaaaaab
	s_lshr_b32 s2, s2, 2
	s_add_i32 s75, s82, 4
	s_mul_i32 s2, s2, 0x18000
	s_sub_i32 s2, s81, s2
	s_cmp_lt_i32 s82, s78
	v_add_u32_e32 v139, s2, v96
	v_add_u32_e32 v138, s2, v97
	v_add_u32_e32 v137, s2, v98
	v_add_u32_e32 v136, s2, v99
	v_add3_u32 v134, s2, v100, v101
	v_add3_u32 v133, s2, v102, v101
	v_add3_u32 v129, s2, v103, v101
	v_add3_u32 v128, s2, v104, v101
	v_add3_u32 v125, s2, v105, v101
	v_add3_u32 v124, s2, v106, v101
	v_add3_u32 v121, s2, v107, v101
	v_add3_u32 v120, s2, v108, v101
	v_add3_u32 v118, s2, v110, v101
	v_add3_u32 v119, s2, v111, v101
	v_add3_u32 v122, s2, v112, v101
	v_add3_u32 v123, s2, v113, v101
	v_add3_u32 v126, s2, v114, v101
	v_add3_u32 v127, s2, v115, v101
	v_add3_u32 v132, s2, v116, v101
	v_add3_u32 v135, s2, v117, v101
	s_cselect_b64 s[2:3], -1, 0
	s_and_b64 vcc, s[2:3], exec
	s_cselect_b32 s2, s75, s79
	s_cmp_lt_i32 s2, s78
	s_cselect_b32 s3, 0, s78
	s_cselect_b32 s75, s77, 0x2000
	s_sub_i32 s2, s2, s3
	s_lshl_b32 s2, s2, 6
	s_add_i32 s2, s2, s75
	s_add_i32 s3, s81, s74
	s_add_i32 m0, s3, 0
	v_mad_i64_i32 v[34:35], s[2:3], s2, v249, v[92:93]
	v_lshl_add_u64 v[36:37], v[34:35], 0, s[86:87]
	s_add_i32 s1, s81, s1
	global_load_lds_dwordx4 v[36:37], off
	v_lshl_add_u64 v[34:35], v[34:35], 0, s[96:97]
	s_add_i32 m0, s1, 0
	s_mov_b64 s[74:75], -1
	global_load_lds_dwordx4 v[34:35], off
	s_waitcnt vmcnt(8)
	s_waitcnt lgkmcnt(0)
	s_barrier
	s_cbranch_vccnz .LBB0_620
	s_mov_b32 s1, 0
	v_add_u32_e32 v38, s1, v139
	ds_read_b128 v[34:37], v38
	ds_read_b128 v[50:53], v38 offset:4096
	v_add_u32_e32 v58, s1, v138
	ds_read_b128 v[54:57], v58
	ds_read_b128 v[84:87], v58 offset:4096
	v_add_u32_e32 v59, s1, v137
	v_add_u32_e32 v58, s1, v136
	s_waitcnt lgkmcnt(0)
	v_mfma_f32_32x32x16_bf16 v[34:49], v[34:37], v[68:71], 0
	ds_read_b128 v[88:91], v59 offset:4096
	v_mfma_f32_32x32x16_bf16 v[34:49], v[54:57], v[72:75], v[34:49]
	ds_read_b128 v[54:57], v59
	s_waitcnt lgkmcnt(0)
	v_mfma_f32_32x32x16_bf16 v[34:49], v[54:57], v[76:79], v[34:49]
	ds_read_b128 v[54:57], v58
	ds_read_b128 v[140:143], v58 offset:4096
	s_waitcnt lgkmcnt(0)
	v_mfma_f32_32x32x16_bf16 v[34:49], v[54:57], v[80:83], v[34:49]
	v_mfma_f32_32x32x16_bf16 v[50:65], v[50:53], v[68:71], 0
	v_mfma_f32_32x32x16_bf16 v[50:65], v[84:87], v[72:75], v[50:65]
	v_mfma_f32_32x32x16_bf16 v[50:65], v[88:91], v[76:79], v[50:65]
	v_mfma_f32_32x32x16_bf16 v[50:65], v[140:143], v[80:83], v[50:65]
	s_nop 7
	s_mov_b32 s1, 0xf149f2ca
	v_max3_f32 v66, v34, v35, v36
	v_max3_f32 v66, v66, v37, v38
	v_max3_f32 v66, v66, v39, v40
	v_max3_f32 v66, v66, v41, v42
	v_max3_f32 v66, v66, v43, v44
	v_max3_f32 v66, v66, v45, v46
	v_max3_f32 v66, v66, v47, v48
	v_max3_f32 v66, v66, v49, v50
	v_max3_f32 v66, v66, v51, v52
	v_max3_f32 v66, v66, v53, v54
	v_max3_f32 v66, v66, v55, v56
	v_max3_f32 v66, v66, v57, v58
	v_max3_f32 v66, v66, v59, v60
	v_max3_f32 v66, v66, v61, v62
	v_max3_f32 v66, v66, v63, v64
	v_max_f32_e32 v66, v66, v65
	v_cmp_lt_i32_e32 vcc, v242, v241
	v_mul_f32_e32 v66, 0x3e38aa3b, v66
	v_max_f32_e32 v66, s1, v66
	v_cndmask_b32_e32 v84, v240, v242, vcc
	v_lshlrev_b32_e32 v84, 2, v84
	ds_bpermute_b32 v84, v84, v66
	s_waitcnt lgkmcnt(0)
; #define LAS __attribute__((address_space(3)))
; #define MFMA32(a, b, c) __builtin_amdgcn_mfma_f32_32x32x16_bf16((a), (b), (c), 0, 0, 0)
; __device__ __forceinline__ unsigned cvtpk(float lo, float hi) { return pg8::cvt_pk_bf16(lo, hi); }
; template <class ScoreFn>
; __device__ __forceinline__ void attn_step(AttnState& st, const bf16x8 (&qf)[4], LAS unsigned char* kb, LAS unsigned char* vb, int lane, const ScoreFn& sf) {
;     ...
;     mt = fmaxf(mt, __shfl_xor(mt, 32));
;     const float mn = fmaxf(st.m, mt), alpha = __builtin_amdgcn_exp2f(st.m - mn);
;     float ps = 0.f;
; #pragma unroll
;     for (int i = 0; i < 16; ++i) { s0[i] = __builtin_amdgcn_exp2f(s0[i] - mn); s1[i] = __builtin_amdgcn_exp2f(s1[i] - mn); ps += s0[i] + s1[i]; }
;     st.l = st.l * alpha + ps; st.m = mn;
; #pragma unroll
;     for (int i = 0; i < 16; ++i) { st.o0[i] *= alpha; st.o1[i] *= alpha; }
;     __builtin_amdgcn_sched_barrier(0);
;     v4u pw[4];
;     pw[0].x = cvtpk(s0[0], s0[1]); pw[0].y = cvtpk(s0[2], s0[3]); pw[0].z = cvtpk(s0[4], s0[5]); pw[0].w = cvtpk(s0[6], s0[7]);
;     pw[1].x = cvtpk(s0[8], s0[9]); pw[1].y = cvtpk(s0[10], s0[11]); pw[1].z = cvtpk(s0[12], s0[13]); pw[1].w = cvtpk(s0[14], s0[15]);
;     pw[2].x = cvtpk(s1[0], s1[1]); pw[2].y = cvtpk(s1[2], s1[3]); pw[2].z = cvtpk(s1[4], s1[5]); pw[2].w = cvtpk(s1[6], s1[7]);
;     pw[3].x = cvtpk(s1[8], s1[9]); pw[3].y = cvtpk(s1[10], s1[11]); pw[3].z = cvtpk(s1[12], s1[13]); pw[3].w = cvtpk(s1[14], s1[15]);
;     const int i16 = lane & 15, q = i16 >> 2, p = i16 & 3, dhalf = (lane >> 4) & 1;
;     LAS unsigned char* vrow = vb + (4 * h + q) * KVP + (p & 1) * 8;
;     LAS unsigned char* vp0 = vrow + (((2 * dhalf + (p >> 1)) ^ (4 * h + q)) << 4); LAS unsigned char* vp1 = vrow + (((4 + 2 * dhalf + (p >> 1)) ^ (4 * h + q)) << 4);
; #pragma unroll
;     for (int ks = 0; ks < 4; ++ks) {
;         const s16x4 l0 = tr_read(vp0 + (16 * ks) * KVP), h0 = tr_read(vp0 + (16 * ks + 8) * KVP);
;         const s16x4 l1 = tr_read(vp1 + (16 * ks) * KVP), h1 = tr_read(vp1 + (16 * ks + 8) * KVP);
;         const bf16x8 v0 = (bf16x8){l0[0], l0[1], l0[2], l0[3], h0[0], h0[1], h0[2], h0[3]};
;         const bf16x8 v1 = (bf16x8){l1[0], l1[1], l1[2], l1[3], h1[0], h1[1], h1[2], h1[3]};
;         const bf16x8 pf = __builtin_bit_cast(bf16x8, pw[ks]);
;         st.o0 = MFMA32(v0, pf, st.o0); st.o1 = MFMA32(v1, pf, st.o1);
;     }
	v_max3_f32 v140, v131, v66, v84
	v_pk_fma_f32 v[34:35], v[34:35], s[0:1], v[140:141] op_sel_hi:[1,0,0] neg_lo:[0,0,1] neg_hi:[0,0,1]
	v_pk_fma_f32 v[50:51], v[50:51], s[0:1], v[140:141] op_sel_hi:[1,0,0] neg_lo:[0,0,1] neg_hi:[0,0,1]
	v_exp_f32_e32 v142, v34
	v_exp_f32_e32 v165, v50
	v_exp_f32_e32 v66, v35
	v_exp_f32_e32 v84, v51
	v_add_f32_e32 v85, v165, v142
	v_pk_add_f32 v[34:35], v[84:85], v[66:67]
	s_nop 0
	v_pk_add_f32 v[86:87], v[34:35], v[34:35] op_sel_hi:[0,1]
	v_pk_fma_f32 v[36:37], v[36:37], s[0:1], v[140:141] op_sel_hi:[1,0,0] neg_lo:[0,0,1] neg_hi:[0,0,1]
	v_pk_fma_f32 v[52:53], v[52:53], s[0:1], v[140:141] op_sel_hi:[1,0,0] neg_lo:[0,0,1] neg_hi:[0,0,1]
	v_exp_f32_e32 v85, v36
	v_exp_f32_e32 v170, v52
	v_exp_f32_e32 v86, v37
	v_exp_f32_e32 v90, v53
	v_add_f32_e32 v91, v170, v85
	v_pk_add_f32 v[34:35], v[90:91], v[86:87]
	s_nop 0
	v_pk_add_f32 v[88:89], v[34:35], v[34:35] op_sel_hi:[0,1]
	v_pk_fma_f32 v[38:39], v[38:39], s[0:1], v[140:141] op_sel_hi:[1,0,0] neg_lo:[0,0,1] neg_hi:[0,0,1]
	v_pk_fma_f32 v[54:55], v[54:55], s[0:1], v[140:141] op_sel_hi:[1,0,0] neg_lo:[0,0,1] neg_hi:[0,0,1]
	v_exp_f32_e32 v87, v38
	v_exp_f32_e32 v91, v54
	v_exp_f32_e32 v88, v39
	v_exp_f32_e32 v150, v55
	v_add_f32_e32 v151, v91, v87
	v_pk_add_f32 v[34:35], v[150:151], v[88:89]
	s_nop 0
	v_pk_add_f32 v[146:147], v[34:35], v[34:35] op_sel_hi:[0,1]
	v_pk_fma_f32 v[40:41], v[40:41], s[0:1], v[140:141] op_sel_hi:[1,0,0] neg_lo:[0,0,1] neg_hi:[0,0,1]
	v_pk_fma_f32 v[56:57], v[56:57], s[0:1], v[140:141] op_sel_hi:[1,0,0] neg_lo:[0,0,1] neg_hi:[0,0,1]
	v_exp_f32_e32 v89, v40
	v_exp_f32_e32 v151, v56
	v_exp_f32_e32 v146, v41
	v_exp_f32_e32 v152, v57
	v_add_f32_e32 v153, v151, v89
	v_pk_add_f32 v[34:35], v[152:153], v[146:147]
	s_nop 0
	v_pk_add_f32 v[148:149], v[34:35], v[34:35] op_sel_hi:[0,1]
	v_pk_fma_f32 v[42:43], v[42:43], s[0:1], v[140:141] op_sel_hi:[1,0,0] neg_lo:[0,0,1] neg_hi:[0,0,1]
	v_pk_fma_f32 v[58:59], v[58:59], s[0:1], v[140:141] op_sel_hi:[1,0,0] neg_lo:[0,0,1] neg_hi:[0,0,1]
	v_exp_f32_e32 v147, v42
	v_exp_f32_e32 v153, v58
	v_exp_f32_e32 v148, v43
	v_exp_f32_e32 v154, v59
	v_add_f32_e32 v155, v153, v147
	v_pk_add_f32 v[34:35], v[154:155], v[148:149]
	s_nop 0
	v_pk_add_f32 v[156:157], v[34:35], v[34:35] op_sel_hi:[0,1]
	v_pk_fma_f32 v[44:45], v[44:45], s[0:1], v[140:141] op_sel_hi:[1,0,0] neg_lo:[0,0,1] neg_hi:[0,0,1]
	v_pk_fma_f32 v[60:61], v[60:61], s[0:1], v[140:141] op_sel_hi:[1,0,0] neg_lo:[0,0,1] neg_hi:[0,0,1]
	v_exp_f32_e32 v149, v44
	v_exp_f32_e32 v155, v60
	v_exp_f32_e32 v156, v45
	v_exp_f32_e32 v158, v61
	v_add_f32_e32 v159, v155, v149
	v_pk_add_f32 v[34:35], v[158:159], v[156:157]
	s_nop 0
	v_pk_add_f32 v[160:161], v[34:35], v[34:35] op_sel_hi:[0,1]
	v_pk_fma_f32 v[46:47], v[46:47], s[0:1], v[140:141] op_sel_hi:[1,0,0] neg_lo:[0,0,1] neg_hi:[0,0,1]
	v_pk_fma_f32 v[62:63], v[62:63], s[0:1], v[140:141] op_sel_hi:[1,0,0] neg_lo:[0,0,1] neg_hi:[0,0,1]
	v_exp_f32_e32 v157, v46
	v_exp_f32_e32 v159, v62
	v_exp_f32_e32 v160, v47
	v_exp_f32_e32 v162, v63
	v_add_f32_e32 v163, v159, v157
	v_pk_add_f32 v[34:35], v[162:163], v[160:161]
	s_nop 0
	v_pk_add_f32 v[166:167], v[34:35], v[34:35] op_sel_hi:[0,1]
	v_pk_fma_f32 v[48:49], v[48:49], s[0:1], v[140:141] op_sel_hi:[1,0,0] neg_lo:[0,0,1] neg_hi:[0,0,1]
	v_pk_fma_f32 v[64:65], v[64:65], s[0:1], v[140:141] op_sel_hi:[1,0,0] neg_lo:[0,0,1] neg_hi:[0,0,1]
	v_exp_f32_e32 v161, v48
	v_exp_f32_e32 v163, v64
	v_exp_f32_e32 v166, v49
	v_exp_f32_e32 v168, v65
	v_sub_f32_e32 v34, v131, v140
	v_exp_f32_e32 v50, v34
	v_add_f32_e32 v169, v163, v161
	v_pk_add_f32 v[34:35], v[168:169], v[166:167]
	v_pk_mul_f32 v[48:49], v[32:33], v[50:51] op_sel_hi:[1,0]
	v_add_f32_e32 v141, v34, v35
	v_fmac_f32_e32 v141, v130, v50
	v_pk_mul_f32 v[46:47], v[30:31], v[50:51] op_sel_hi:[1,0]
	v_pk_mul_f32 v[44:45], v[28:29], v[50:51] op_sel_hi:[1,0]
	v_pk_mul_f32 v[42:43], v[26:27], v[50:51] op_sel_hi:[1,0]
	v_pk_mul_f32 v[40:41], v[24:25], v[50:51] op_sel_hi:[1,0]
	v_pk_mul_f32 v[38:39], v[22:23], v[50:51] op_sel_hi:[1,0]
	v_pk_mul_f32 v[36:37], v[20:21], v[50:51] op_sel_hi:[1,0]
	v_pk_mul_f32 v[34:35], v[18:19], v[50:51] op_sel_hi:[1,0]
	v_pk_mul_f32 v[64:65], v[16:17], v[50:51] op_sel_hi:[1,0]
	v_pk_mul_f32 v[62:63], v[14:15], v[50:51] op_sel_hi:[1,0]
	v_pk_mul_f32 v[60:61], v[12:13], v[50:51] op_sel_hi:[1,0]
	v_pk_mul_f32 v[58:59], v[10:11], v[50:51] op_sel_hi:[1,0]
	v_pk_mul_f32 v[56:57], v[8:9], v[50:51] op_sel_hi:[1,0]
	v_pk_mul_f32 v[54:55], v[6:7], v[50:51] op_sel_hi:[1,0]
	v_pk_mul_f32 v[52:53], v[4:5], v[50:51] op_sel_hi:[1,0]
	v_pk_mul_f32 v[50:51], v[2:3], v[50:51] op_sel_hi:[1,0]
	v_cvt_pk_bf16_f32 v142, v142, v66
	v_cvt_pk_bf16_f32 v144, v87, v88
	v_cvt_pk_bf16_f32 v145, v89, v146
	v_cvt_pk_bf16_f32 v88, v165, v84
	v_cvt_pk_bf16_f32 v89, v170, v90
	v_cvt_pk_bf16_f32 v90, v91, v150
	v_cvt_pk_bf16_f32 v91, v151, v152
	v_cvt_pk_bf16_f32 v84, v153, v154
	ds_read_b64_tr_b16 v[150:151], v134
	v_cvt_pk_bf16_f32 v143, v85, v86
	v_cvt_pk_bf16_f32 v85, v155, v158
	ds_read_b64_tr_b16 v[152:153], v133
	ds_read_b64_tr_b16 v[154:155], v135
	v_cvt_pk_bf16_f32 v146, v147, v148
	v_cvt_pk_bf16_f32 v147, v149, v156
	v_cvt_pk_bf16_f32 v148, v157, v160
	ds_read_b64_tr_b16 v[156:157], v132
	s_waitcnt lgkmcnt(2)
	v_mfma_f32_32x32x16_bf16 v[34:49], v[150:153], v[142:145], v[34:49]
	v_cvt_pk_bf16_f32 v149, v161, v166
	v_cvt_pk_bf16_f32 v86, v159, v162
	v_cvt_pk_bf16_f32 v87, v163, v168
	s_mov_b64 s[74:75], 0
	s_waitcnt lgkmcnt(0)
	v_mfma_f32_32x32x16_bf16 v[50:65], v[154:157], v[142:145], v[50:65]
	ds_read_b64_tr_b16 v[142:143], v129
	ds_read_b64_tr_b16 v[144:145], v128
	ds_read_b64_tr_b16 v[150:151], v127
	ds_read_b64_tr_b16 v[152:153], v126
	s_waitcnt lgkmcnt(2)
	v_mfma_f32_32x32x16_bf16 v[34:49], v[142:145], v[146:149], v[34:49]
	ds_read_b64_tr_b16 v[142:143], v125
	ds_read_b64_tr_b16 v[144:145], v124
	s_waitcnt lgkmcnt(2)
	v_mfma_f32_32x32x16_bf16 v[50:65], v[150:153], v[146:149], v[50:65]
	ds_read_b64_tr_b16 v[146:147], v123
	ds_read_b64_tr_b16 v[148:149], v122
	s_waitcnt lgkmcnt(2)
	v_mfma_f32_32x32x16_bf16 v[34:49], v[142:145], v[88:91], v[34:49]
	s_waitcnt lgkmcnt(0)
	v_mfma_f32_32x32x16_bf16 v[50:65], v[146:149], v[88:91], v[50:65]
	ds_read_b64_tr_b16 v[88:89], v121
	ds_read_b64_tr_b16 v[90:91], v120
	ds_read_b64_tr_b16 v[142:143], v119
	ds_read_b64_tr_b16 v[144:145], v118
	s_waitcnt lgkmcnt(2)
	v_mfma_f32_32x32x16_bf16 v[34:49], v[88:91], v[84:87], v[34:49]
	s_waitcnt lgkmcnt(0)
	v_mfma_f32_32x32x16_bf16 v[50:65], v[142:145], v[84:87], v[50:65]
